# prologue: kscale loads issued before the element-load wait (27+5, at most 63 outstanding) so L2 and HBM latencies overlap
# speedup vs baseline: 1.0038x; 1.0020x over previous
; #define LDS_WAIT() asm volatile("s_waitcnt lgkmcnt(0)" ::: "memory")
; __device__ __forceinline__ void tr_matrix(const float* W, int ldw, int K, int N, bf16* WT, int mode, const float* kscale, float* scr, int gw, int NGW, int lane) {
;     ...
;     for (int it = gw; it < nitems; it += NGW) {
;         const int kb = it / nblk, nb = it % nblk, k0 = 64 * kb, n0 = 32 * nb;
; #pragma unroll
;         for (int i = 0; i < 32; ++i) { const int kk = 2 * i + (lane >> 5); scr[kk * 33 + (lane & 31)] = kscale ? nx[i] * kscale[k0 + kk] : nx[i]; }
;         if (it + NGW < nitems) { const int kb2 = (it + NGW) / nblk, nb2 = (it + NGW) % nblk;
; #pragma unroll
;             for (int i = 0; i < 32; ++i) { const int kk = 2 * i + (lane >> 5); nx[i] = W[(size_t)(64 * kb2 + kk) * ldw + 32 * nb2 + (lane & 31)]; } }
;         LDS_WAIT();
.LBB0_36:
	v_sub_u32_e32 v51, 0, v86
	v_max_i32_e32 v51, v86, v51
	v_mul_hi_u32 v87, v51, v3
	v_mul_lo_u32 v88, v87, s6
	v_sub_u32_e32 v51, v51, v88
	v_add_u32_e32 v88, 1, v87
	v_cmp_le_u32_e32 vcc, s6, v51
	v_ashrrev_i32_e32 v50, 31, v86
	s_nop 0
	v_cndmask_b32_e32 v87, v87, v88, vcc
	v_subrev_u32_e32 v88, s6, v51
	v_cndmask_b32_e32 v51, v51, v88, vcc
	v_add_u32_e32 v88, 1, v87
	v_cmp_le_u32_e32 vcc, s6, v51
	s_nop 1
	v_cndmask_b32_e32 v51, v87, v88, vcc
	v_xor_b32_e32 v51, v51, v50
	v_sub_u32_e32 v87, v51, v50
	v_cndmask_b32_e64 v51, 0, 1, s[22:23]
	v_lshlrev_b32_e32 v50, 6, v87
	v_cmp_ne_u32_e64 s[4:5], 1, v51
	s_andn2_b64 vcc, exec, s[22:23]
	s_cbranch_vccnz .Lks_none
	v_or_b32_e32 v88, v50, v36
	v_ashrrev_i32_e32 v89, 31, v88
	v_lshl_add_u64 v[88:89], v[88:89], 2, s[12:13]
	v_ashrrev_i32_e32 v51, 31, v50
	s_waitcnt vmcnt(36)
	global_load_dword v113, v[88:89], off
	global_load_dword v114, v[88:89], off offset:8
	global_load_dword v115, v[88:89], off offset:16
	global_load_dword v116, v[88:89], off offset:24
	global_load_dword v117, v[88:89], off offset:32
	global_load_dword v118, v[88:89], off offset:40
	global_load_dword v119, v[88:89], off offset:48
	global_load_dword v120, v[88:89], off offset:56
	global_load_dword v121, v[88:89], off offset:64
	global_load_dword v122, v[88:89], off offset:72
	global_load_dword v123, v[88:89], off offset:80
	global_load_dword v124, v[88:89], off offset:88
	global_load_dword v125, v[88:89], off offset:96
	global_load_dword v126, v[88:89], off offset:104
	global_load_dword v127, v[88:89], off offset:112
	global_load_dword v128, v[88:89], off offset:120
	global_load_dword v129, v[88:89], off offset:128
	global_load_dword v130, v[88:89], off offset:136
	global_load_dword v131, v[88:89], off offset:144
	global_load_dword v132, v[88:89], off offset:152
	global_load_dword v133, v[88:89], off offset:160
	global_load_dword v134, v[88:89], off offset:168
	global_load_dword v135, v[88:89], off offset:176
	global_load_dword v136, v[88:89], off offset:184
	global_load_dword v137, v[88:89], off offset:192
	global_load_dword v138, v[88:89], off offset:200
	global_load_dword v139, v[88:89], off offset:208
	s_waitcnt vmcnt(58)
	global_load_dword v140, v[88:89], off offset:216
	global_load_dword v141, v[88:89], off offset:224
	global_load_dword v142, v[88:89], off offset:232
	global_load_dword v143, v[88:89], off offset:240
	global_load_dword v148, v[88:89], off offset:248
	s_waitcnt vmcnt(31)
	v_mul_f32_e32 v89, v4, v113
	ds_write_b32 v52, v89
	s_waitcnt vmcnt(30)
	v_mul_f32_e32 v88, v5, v114
	ds_write_b32 v53, v88
	s_waitcnt vmcnt(29)
	v_mul_f32_e32 v89, v6, v115
	ds_write_b32 v54, v89
	s_waitcnt vmcnt(28)
	v_mul_f32_e32 v88, v7, v116
	ds_write_b32 v55, v88
	s_waitcnt vmcnt(27)
	v_mul_f32_e32 v89, v8, v117
	ds_write_b32 v56, v89
	s_waitcnt vmcnt(26)
	v_mul_f32_e32 v88, v9, v118
	ds_write_b32 v57, v88
	s_waitcnt vmcnt(25)
	v_mul_f32_e32 v89, v10, v119
	ds_write_b32 v58, v89
	s_waitcnt vmcnt(24)
	v_mul_f32_e32 v88, v11, v120
	ds_write_b32 v59, v88
	s_waitcnt vmcnt(23)
	v_mul_f32_e32 v89, v12, v121
	ds_write_b32 v60, v89
	s_waitcnt vmcnt(22)
	v_mul_f32_e32 v88, v13, v122
	ds_write_b32 v61, v88
	s_waitcnt vmcnt(21)
	v_mul_f32_e32 v89, v14, v123
	ds_write_b32 v62, v89
	s_waitcnt vmcnt(20)
	v_mul_f32_e32 v88, v15, v124
	ds_write_b32 v63, v88
	s_waitcnt vmcnt(19)
	v_mul_f32_e32 v89, v16, v125
	ds_write_b32 v64, v89
	s_waitcnt vmcnt(18)
	v_mul_f32_e32 v88, v17, v126
	ds_write_b32 v65, v88
	s_waitcnt vmcnt(17)
	v_mul_f32_e32 v89, v18, v127
	ds_write_b32 v66, v89
	s_waitcnt vmcnt(16)
	v_mul_f32_e32 v88, v19, v128
	ds_write_b32 v67, v88
	s_waitcnt vmcnt(15)
	v_mul_f32_e32 v89, v20, v129
	ds_write_b32 v68, v89
	s_waitcnt vmcnt(14)
	v_mul_f32_e32 v88, v21, v130
	ds_write_b32 v69, v88
	s_waitcnt vmcnt(13)
	v_mul_f32_e32 v89, v22, v131
	ds_write_b32 v70, v89
	s_waitcnt vmcnt(12)
	v_mul_f32_e32 v88, v23, v132
	ds_write_b32 v71, v88
	s_waitcnt vmcnt(11)
	v_mul_f32_e32 v89, v24, v133
	ds_write_b32 v72, v89
	s_waitcnt vmcnt(10)
	v_mul_f32_e32 v88, v25, v134
	ds_write_b32 v73, v88
	s_waitcnt vmcnt(9)
	v_mul_f32_e32 v89, v26, v135
	ds_write_b32 v74, v89
	s_waitcnt vmcnt(8)
	v_mul_f32_e32 v88, v27, v136
	ds_write_b32 v75, v88
	s_waitcnt vmcnt(7)
	v_mul_f32_e32 v89, v28, v137
	ds_write_b32 v76, v89
	s_waitcnt vmcnt(6)
	v_mul_f32_e32 v88, v29, v138
	ds_write_b32 v77, v88
	s_waitcnt vmcnt(5)
	v_mul_f32_e32 v89, v30, v139
	ds_write_b32 v78, v89
	s_waitcnt vmcnt(4)
	v_mul_f32_e32 v88, v31, v140
	ds_write_b32 v79, v88
	s_waitcnt vmcnt(3)
	v_mul_f32_e32 v89, v32, v141
	ds_write_b32 v80, v89
	s_waitcnt vmcnt(2)
	v_mul_f32_e32 v88, v33, v142
	ds_write_b32 v81, v88
	s_waitcnt vmcnt(1)
	v_mul_f32_e32 v89, v34, v143
	ds_write_b32 v82, v89
	s_waitcnt vmcnt(0)
	v_mul_f32_e32 v88, v35, v148
	s_branch .LBB0_100
